# plus static s_setprio 1 for waves 4-7 inside the differential-attention tile loop
# baseline (speedup 1.0000x reference)
; __device__ __forceinline__ void flash_da2(LAS unsigned char* lds, const bf16* __restrict__ Qw, const bf16* __restrict__ Kb, const bf16* __restrict__ VTb,
;                                           int NT, int qpos_w, f32x16 (&o)[4], float& mref, float& lsum) {
;     const int tid = threadIdx.x, lane = tid & 63, r32 = lane & 31, hi = lane >> 5;
;     const int wid = __builtin_amdgcn_readfirstlane(tid >> 6);
;     const unsigned lds0 = (unsigned)(uintptr_t)lds;
;     bf16x8 qf[4];
; #pragma unroll
;     for (int d0 = 0; d0 < 4; ++d0) qf[d0] = *(const bf16x8*)(Qw + (size_t)r32 * 64 + d0 * 16 + hi * 8);
;     const int lrow = wid * 8 + (lane >> 3), pch = lane & 7, lch = pch ^ ((lrow >> 1) & 7);
;     const int rho = lrow & 31, key = (lrow & 32) + 16 * ((rho >> 2) & 1) + 4 * (rho >> 3) + (rho & 3);
;     const bf16* ksrc = Kb + key * 64 + lch * 8;
;     const bf16* vsrc = VTb + lrow * 64 + lch * 8;
;     const unsigned kdst = lds0 + A_K + wid * 1024, vdst = lds0 + A_V + wid * 1024;
;     const int sw = (r32 >> 1) & 7;
;     unsigned kaddr[4], vaddr[4];
; #pragma unroll
;     for (int d0 = 0; d0 < 4; ++d0) kaddr[d0] = A_K + r32 * 128 + (((2 * d0 + hi) ^ sw) << 4);
; #pragma unroll
;     for (int c4 = 0; c4 < 4; ++c4) vaddr[c4] = A_V + r32 * 128 + (((4 * (c4 >> 1) + 2 * hi + (c4 & 1)) ^ sw) << 4);
; #pragma unroll
;     for (int j = 0; j < 2; ++j) {
;         glds16(ksrc + (size_t)j * 4096, (unsigned)__builtin_amdgcn_readfirstlane(kdst + j * 8192));
;         glds16(vsrc + (size_t)j * 8192, (unsigned)__builtin_amdgcn_readfirstlane(vdst + j * 16384));
;         glds16(vsrc + (size_t)j * 8192 + 4096, (unsigned)__builtin_amdgcn_readfirstlane(vdst + j * 16384 + 8192));
;     }
;     asm volatile("" :: "v"(qf[0]), "v"(qf[1]), "v"(qf[2]), "v"(qf[3]));
;     asm volatile("s_waitcnt vmcnt(0) lgkmcnt(0)\n\ts_barrier" ::: "memory");
;     int cls_cur = 0; float cb = 0.f;
.LBB0_426:
	s_mul_i32 s8, s51, s8
	s_xor_b64 s[58:59], s[10:11], -1
	s_lshl_b64 s[10:11], s[8:9], 1
	v_lshl_add_u64 v[2:3], v[158:159], 0, s[10:11]
	global_load_dwordx4 v[112:115], v[2:3], off
	global_load_dwordx4 v[116:119], v[2:3], off offset:32
	global_load_dwordx4 v[120:123], v[2:3], off offset:64
	global_load_dwordx4 v[124:127], v[2:3], off offset:96
	s_add_u32 s52, s88, s10
	v_readfirstlane_b32 s35, v151
	s_addc_u32 s53, s89, s11
	s_lshr_b32 s10, s35, 6
	s_lshl_b32 s11, s10, 3
	s_lshr_b32 s35, s35, 4
	v_or_b32_e32 v0, s11, v195
	s_and_b32 s11, s11, 32
	s_and_b32 s35, s35, 12
	s_or_b32 s11, s11, s35
	v_lshrrev_b32_e32 v8, 1, v0
	v_or_b32_e32 v4, s11, v196
	v_lshlrev_b32_e32 v0, 7, v0
	v_xor_b32_e32 v6, v8, v151
	v_lshl_add_u64 v[2:3], s[54:55], 0, v[0:1]
	v_lshlrev_b32_e32 v0, 7, v4
	v_lshl_add_u64 v[4:5], s[52:53], 0, v[0:1]
	v_lshlrev_b32_e32 v0, 4, v6
	s_lshl_b32 s11, s10, 10
	v_and_b32_e32 v0, 0x70, v0
	s_add_i32 s35, s11, 0
	v_lshl_add_u64 v[4:5], v[4:5], 0, v[0:1]
	s_mov_b32 s11, m0
	s_mov_b32 m0, s35
	s_nop 0
	global_load_lds_dwordx4 v[4:5], off
	s_mov_b32 m0, s11
	v_lshl_add_u64 v[2:3], v[2:3], 0, v[0:1]
	s_add_i32 s52, s35, 0x8000
	s_mov_b32 s11, m0
	s_mov_b32 m0, s52
	s_nop 0
	global_load_lds_dwordx4 v[2:3], off
	s_mov_b32 m0, s11
	v_lshl_add_u64 v[6:7], v[2:3], 0, s[38:39]
	s_add_i32 s11, s52, 0x2000
	s_mov_b32 s53, m0
	s_mov_b32 m0, s11
	s_nop 0
	global_load_lds_dwordx4 v[6:7], off
	s_mov_b32 m0, s53
	v_lshl_add_u64 v[6:7], v[4:5], 0, s[38:39]
	s_add_i32 s11, s35, 0x2000
	s_mov_b32 s53, m0
	s_mov_b32 m0, s11
	s_nop 0
	global_load_lds_dwordx4 v[6:7], off
	s_mov_b32 m0, s53
	v_lshl_add_u64 v[6:7], v[2:3], 0, s[40:41]
	s_add_i32 s11, s35, 0xc000
	s_mov_b32 s53, m0
	s_mov_b32 m0, s11
	s_nop 0
	global_load_lds_dwordx4 v[6:7], off
	s_mov_b32 m0, s53
	v_lshl_add_u64 v[2:3], v[2:3], 0, s[42:43]
	v_bitop3_b32 v0, v8, 7, v151 bitop3:0x48
	s_add_i32 s11, s35, 0xe000
	s_mov_b32 s53, m0
	s_mov_b32 m0, s11
	s_nop 0
	global_load_lds_dwordx4 v[2:3], off
	s_mov_b32 m0, s53
	v_lshlrev_b32_e32 v0, 4, v0
	v_lshl_or_b32 v2, s10, 9, v216
	v_mov_b32_e32 v3, v1
	v_lshl_add_u64 v[2:3], v[2:3], 1, v[0:1]
	v_mov_b32_e32 v14, v1
	v_mov_b32_e32 v15, v1
	v_lshl_add_u64 v[160:161], s[56:57], 0, v[2:3]
	v_lshl_add_u64 v[162:163], v[4:5], 0, s[42:43]
	v_mov_b32_e32 v0, v1
	v_mov_b32_e32 v2, v1
	v_mov_b32_e32 v3, v1
	v_mov_b32_e32 v4, v1
	v_mov_b32_e32 v5, v1
	v_mov_b32_e32 v6, v1
	v_mov_b32_e32 v7, v1
	v_mov_b32_e32 v8, v1
	v_mov_b32_e32 v9, v1
	v_mov_b32_e32 v10, v1
	v_mov_b32_e32 v11, v1
	v_mov_b32_e32 v12, v1
	v_mov_b32_e32 v13, v1
	v_mov_b64_e32 v[30:31], v[14:15]
	v_mov_b64_e32 v[46:47], v[14:15]
	v_mov_b64_e32 v[62:63], v[14:15]
	v_mov_b64_e32 v[78:79], v[14:15]
	s_mov_b32 s8, 3
	s_mov_b32 s53, s91
	v_mov_b32_e32 v223, v221
	v_mov_b64_e32 v[28:29], v[12:13]
	v_mov_b64_e32 v[26:27], v[10:11]
	v_mov_b64_e32 v[24:25], v[8:9]
	v_mov_b64_e32 v[22:23], v[6:7]
	v_mov_b64_e32 v[20:21], v[4:5]
	v_mov_b64_e32 v[18:19], v[2:3]
	v_mov_b64_e32 v[16:17], v[0:1]
	v_mov_b64_e32 v[44:45], v[12:13]
	v_mov_b64_e32 v[42:43], v[10:11]
	v_mov_b64_e32 v[40:41], v[8:9]
	v_mov_b64_e32 v[38:39], v[6:7]
	s_waitcnt vmcnt(0)
	s_waitcnt vmcnt(0) lgkmcnt(0)
	s_barrier
	v_readfirstlane_b32 s98, v151
	s_bitcmp1_b32 s98, 8
	s_cbranch_scc0 .Lda_prio_skip
	s_setprio 1
.Lda_prio_skip:
	v_mov_b64_e32 v[36:37], v[4:5]
	v_mov_b64_e32 v[34:35], v[2:3]
	v_mov_b64_e32 v[32:33], v[0:1]
	v_mov_b64_e32 v[60:61], v[12:13]
	v_mov_b64_e32 v[58:59], v[10:11]
	v_mov_b64_e32 v[56:57], v[8:9]
	v_mov_b64_e32 v[54:55], v[6:7]
	v_mov_b64_e32 v[52:53], v[4:5]
	v_mov_b64_e32 v[50:51], v[2:3]
	v_mov_b64_e32 v[48:49], v[0:1]
	v_mov_b64_e32 v[76:77], v[12:13]
	v_mov_b64_e32 v[74:75], v[10:11]
	v_mov_b64_e32 v[72:73], v[8:9]
	v_mov_b64_e32 v[70:71], v[6:7]
	v_mov_b64_e32 v[68:69], v[4:5]
	v_mov_b64_e32 v[66:67], v[2:3]
	v_mov_b64_e32 v[64:65], v[0:1]
	v_mov_b32_e32 v224, 0
	v_mov_b32_e32 v0, 0
	v_mov_b32_e32 v225, 0
	s_mov_b32 s10, 0
	s_branch .LBB0_428

; __device__ __forceinline__ float hsum(float v) { auto rr = __builtin_amdgcn_permlane32_swap(__float_as_uint(v), __float_as_uint(v), false, false); return __uint_as_float(rr[0]) + __uint_as_float(rr[1]); }
; __device__ __forceinline__ void da_unit(LAS unsigned char* lds, const AttnP& P, int seqbase, int S, int h, int qb, float lam) {
;     ...
;             const float inv = lam / hsum(l);
; #pragma unroll
;             for (int db = 0; db < 4; ++db)
; #pragma unroll
;                 for (int g = 0; g < 4; ++g) {
;                     const f32x4 st = stash[db * 4 + g];
; #pragma unroll
;                     for (int e = 0; e < 4; ++e) { const float a = st[e] - o[db][4 * g + e] * inv; o[db][4 * g + e] = a; ss += a * a; }
;                 }
.LBB0_450:
	s_setprio 0
	v_mov_b32_e32 v2, v151
	s_and_b64 vcc, exec, s[58:59]
	v_lshrrev_b32_e32 v3, 6, v2
	v_and_b32_e32 v2, 63, v2
	v_lshlrev_b32_e32 v3, 14, v3
	v_lshl_or_b32 v246, v2, 4, v3
	v_add_u32_e32 v247, 0x1000, v246
	v_add_u32_e32 v248, 0x2000, v246
	v_add_u32_e32 v249, 0x3000, v246
	s_cbranch_vccz .LBB0_452
	global_load_dwordx4 v[4:7], v246, s[20:21] offset:0
	global_load_dwordx4 v[8:11], v246, s[20:21] offset:1024
	global_load_dwordx4 v[12:15], v246, s[20:21] offset:2048
	global_load_dwordx4 v[80:83], v246, s[20:21] offset:3072
	global_load_dwordx4 v[84:87], v247, s[20:21] offset:0
	global_load_dwordx4 v[88:91], v247, s[20:21] offset:1024
	global_load_dwordx4 v[92:95], v247, s[20:21] offset:2048
	global_load_dwordx4 v[98:101], v247, s[20:21] offset:3072
	global_load_dwordx4 v[102:105], v248, s[20:21] offset:0
	global_load_dwordx4 v[132:135], v248, s[20:21] offset:1024
	global_load_dwordx4 v[136:139], v248, s[20:21] offset:2048
	global_load_dwordx4 v[140:143], v248, s[20:21] offset:3072
	global_load_dwordx4 v[144:147], v249, s[20:21] offset:3072
	global_load_dwordx4 v[160:163], v249, s[20:21] offset:2048
	global_load_dwordx4 v[164:167], v249, s[20:21] offset:1024
	global_load_dwordx4 v[168:171], v249, s[20:21] offset:0
	v_mov_b32_e32 v96, v0
	v_mov_b32_e32 v97, v0
	s_nop 1
	v_permlane32_swap_b32_e32 v96, v97
	v_add_f32_e32 v96, v96, v97
	v_div_scale_f32 v97, s[10:11], v96, v96, v211
	v_rcp_f32_e32 v106, v97
	v_div_scale_f32 v107, vcc, v211, v96, v211
	v_fma_f32 v108, -v97, v106, 1.0
	v_fmac_f32_e32 v106, v108, v106
	v_mul_f32_e32 v108, v107, v106
	v_fma_f32 v109, -v97, v108, v107
	v_fmac_f32_e32 v108, v109, v106
	v_fma_f32 v97, -v97, v108, v107
	v_div_fmas_f32 v97, v97, v106, v108
	v_div_fixup_f32 v172, v97, v96, v211
	s_waitcnt vmcnt(15)
	v_pk_fma_f32 v[130:131], v[64:65], v[172:173], v[4:5] op_sel_hi:[1,0,1] neg_lo:[1,0,0] neg_hi:[1,0,0]
	v_pk_fma_f32 v[128:129], v[66:67], v[172:173], v[6:7] op_sel_hi:[1,0,1] neg_lo:[1,0,0] neg_hi:[1,0,0]
	s_waitcnt vmcnt(14)
	v_pk_fma_f32 v[126:127], v[68:69], v[172:173], v[8:9] op_sel_hi:[1,0,1] neg_lo:[1,0,0] neg_hi:[1,0,0]
	s_waitcnt vmcnt(12)
	v_pk_fma_f32 v[116:117], v[76:77], v[172:173], v[80:81] op_sel_hi:[1,0,1] neg_lo:[1,0,0] neg_hi:[1,0,0]
	v_pk_mul_f32 v[80:81], v[130:131], v[130:131]
	v_pk_fma_f32 v[114:115], v[78:79], v[172:173], v[82:83] op_sel_hi:[1,0,1] neg_lo:[1,0,0] neg_hi:[1,0,0]
	v_add_f32_e32 v80, v222, v80
	v_pk_mul_f32 v[82:83], v[128:129], v[128:129]
	v_add_f32_e32 v80, v81, v80
	v_add_f32_e32 v80, v82, v80
	s_waitcnt vmcnt(11)
	v_pk_fma_f32 v[118:119], v[48:49], v[172:173], v[84:85] op_sel_hi:[1,0,1] neg_lo:[1,0,0] neg_hi:[1,0,0]
	v_pk_mul_f32 v[84:85], v[126:127], v[126:127]
	v_add_f32_e32 v80, v83, v80
	v_pk_fma_f32 v[124:125], v[70:71], v[172:173], v[10:11] op_sel_hi:[1,0,1] neg_lo:[1,0,0] neg_hi:[1,0,0]
	v_add_f32_e32 v80, v84, v80
	s_waitcnt vmcnt(10)
	v_pk_fma_f32 v[110:111], v[52:53], v[172:173], v[88:89] op_sel_hi:[1,0,1] neg_lo:[1,0,0] neg_hi:[1,0,0]
	v_pk_mul_f32 v[88:89], v[124:125], v[124:125]
	v_add_f32_e32 v80, v85, v80
	v_pk_fma_f32 v[122:123], v[72:73], v[172:173], v[12:13] op_sel_hi:[1,0,1] neg_lo:[1,0,0] neg_hi:[1,0,0]
	v_add_f32_e32 v80, v88, v80
	s_waitcnt vmcnt(9)
	v_pk_fma_f32 v[106:107], v[56:57], v[172:173], v[92:93] op_sel_hi:[1,0,1] neg_lo:[1,0,0] neg_hi:[1,0,0]
	s_waitcnt vmcnt(8)
	v_pk_fma_f32 v[92:93], v[60:61], v[172:173], v[98:99] op_sel_hi:[1,0,1] neg_lo:[1,0,0] neg_hi:[1,0,0]
	v_pk_mul_f32 v[98:99], v[122:123], v[122:123]
	v_add_f32_e32 v80, v89, v80
	v_pk_fma_f32 v[120:121], v[74:75], v[172:173], v[14:15] op_sel_hi:[1,0,1] neg_lo:[1,0,0] neg_hi:[1,0,0]
	v_add_f32_e32 v80, v98, v80
	v_pk_fma_f32 v[108:109], v[54:55], v[172:173], v[90:91] op_sel_hi:[1,0,1] neg_lo:[1,0,0] neg_hi:[1,0,0]
	v_pk_fma_f32 v[90:91], v[62:63], v[172:173], v[100:101] op_sel_hi:[1,0,1] neg_lo:[1,0,0] neg_hi:[1,0,0]
	v_pk_mul_f32 v[100:101], v[120:121], v[120:121]
	v_add_f32_e32 v80, v99, v80
	v_add_f32_e32 v80, v100, v80
	v_pk_fma_f32 v[96:97], v[58:59], v[172:173], v[94:95] op_sel_hi:[1,0,1] neg_lo:[1,0,0] neg_hi:[1,0,0]
	s_waitcnt vmcnt(7)
	v_pk_fma_f32 v[94:95], v[32:33], v[172:173], v[102:103] op_sel_hi:[1,0,1] neg_lo:[1,0,0] neg_hi:[1,0,0]
	v_pk_mul_f32 v[102:103], v[116:117], v[116:117]
	v_add_f32_e32 v80, v101, v80
	v_add_f32_e32 v80, v102, v80
	v_pk_fma_f32 v[112:113], v[50:51], v[172:173], v[86:87] op_sel_hi:[1,0,1] neg_lo:[1,0,0] neg_hi:[1,0,0]
	v_pk_fma_f32 v[86:87], v[34:35], v[172:173], v[104:105] op_sel_hi:[1,0,1] neg_lo:[1,0,0] neg_hi:[1,0,0]
	v_pk_mul_f32 v[104:105], v[114:115], v[114:115]
	v_add_f32_e32 v80, v103, v80
	v_add_f32_e32 v80, v104, v80
	s_waitcnt vmcnt(6)
; __device__ __forceinline__ float hsum(float v) { auto rr = __builtin_amdgcn_permlane32_swap(__float_as_uint(v), __float_as_uint(v), false, false); return __uint_as_float(rr[0]) + __uint_as_float(rr[1]); }
; __device__ __forceinline__ void da_unit(LAS unsigned char* lds, const AttnP& P, int seqbase, int S, int h, int qb, float lam) {
;     ...
;             for (int db = 0; db < 4; ++db)
; #pragma unroll
;                 for (int g = 0; g < 4; ++g) {
;                     const f32x4 st = stash[db * 4 + g];
; #pragma unroll
;                     for (int e = 0; e < 4; ++e) { const float a = st[e] - o[db][4 * g + e] * inv; o[db][4 * g + e] = a; ss += a * a; }
;                 }
;         }
;     }
;     ss = hsum(ss);
	v_pk_fma_f32 v[14:15], v[36:37], v[172:173], v[132:133] op_sel_hi:[1,0,1] neg_lo:[1,0,0] neg_hi:[1,0,0]
	v_pk_mul_f32 v[132:133], v[118:119], v[118:119]
	v_add_f32_e32 v80, v105, v80
	v_add_f32_e32 v80, v132, v80
	v_pk_fma_f32 v[12:13], v[38:39], v[172:173], v[134:135] op_sel_hi:[1,0,1] neg_lo:[1,0,0] neg_hi:[1,0,0]
	v_pk_mul_f32 v[134:135], v[112:113], v[112:113]
	v_add_f32_e32 v80, v133, v80
	v_add_f32_e32 v80, v134, v80
	s_waitcnt vmcnt(5)
	v_pk_fma_f32 v[10:11], v[40:41], v[172:173], v[136:137] op_sel_hi:[1,0,1] neg_lo:[1,0,0] neg_hi:[1,0,0]
	v_pk_mul_f32 v[136:137], v[110:111], v[110:111]
	v_add_f32_e32 v80, v135, v80
	v_add_f32_e32 v80, v136, v80
	v_pk_fma_f32 v[8:9], v[42:43], v[172:173], v[138:139] op_sel_hi:[1,0,1] neg_lo:[1,0,0] neg_hi:[1,0,0]
	v_pk_mul_f32 v[138:139], v[108:109], v[108:109]
	v_add_f32_e32 v80, v137, v80
	v_add_f32_e32 v80, v138, v80
	s_waitcnt vmcnt(4)
	v_pk_fma_f32 v[6:7], v[44:45], v[172:173], v[140:141] op_sel_hi:[1,0,1] neg_lo:[1,0,0] neg_hi:[1,0,0]
	v_pk_mul_f32 v[140:141], v[106:107], v[106:107]
	v_add_f32_e32 v80, v139, v80
	v_add_f32_e32 v80, v140, v80
	v_pk_fma_f32 v[4:5], v[46:47], v[172:173], v[142:143] op_sel_hi:[1,0,1] neg_lo:[1,0,0] neg_hi:[1,0,0]
	v_pk_mul_f32 v[142:143], v[96:97], v[96:97]
	v_add_f32_e32 v80, v141, v80
	v_add_f32_e32 v80, v142, v80
	v_pk_mul_f32 v[174:175], v[92:93], v[92:93]
	v_add_f32_e32 v80, v143, v80
	v_add_f32_e32 v80, v174, v80
	v_pk_mul_f32 v[176:177], v[90:91], v[90:91]
	v_add_f32_e32 v80, v175, v80
	v_add_f32_e32 v80, v176, v80
	v_pk_mul_f32 v[178:179], v[94:95], v[94:95]
	v_add_f32_e32 v80, v177, v80
	v_add_f32_e32 v80, v178, v80
	v_pk_mul_f32 v[180:181], v[86:87], v[86:87]
	v_add_f32_e32 v80, v179, v80
	v_add_f32_e32 v80, v180, v80
	v_pk_mul_f32 v[182:183], v[14:15], v[14:15]
	v_add_f32_e32 v80, v181, v80
	v_add_f32_e32 v80, v182, v80
	v_pk_mul_f32 v[184:185], v[12:13], v[12:13]
	v_add_f32_e32 v80, v183, v80
	v_add_f32_e32 v80, v184, v80
	v_pk_mul_f32 v[186:187], v[10:11], v[10:11]
	v_add_f32_e32 v80, v185, v80
	v_add_f32_e32 v80, v186, v80
	v_pk_mul_f32 v[188:189], v[8:9], v[8:9]
	v_add_f32_e32 v80, v187, v80
	v_add_f32_e32 v80, v188, v80
	v_pk_mul_f32 v[190:191], v[6:7], v[6:7]
	v_add_f32_e32 v80, v189, v80
	v_add_f32_e32 v80, v190, v80
	v_add_f32_e32 v82, v191, v80
	v_pk_mul_f32 v[80:81], v[4:5], v[4:5]
	s_waitcnt vmcnt(0)
	v_pk_fma_f32 v[102:103], v[16:17], v[172:173], v[168:169] op_sel_hi:[1,0,1] neg_lo:[1,0,0] neg_hi:[1,0,0]
	v_add_f32_e32 v80, v80, v82
	v_add_f32_e32 v82, v81, v80
	v_pk_mul_f32 v[80:81], v[102:103], v[102:103]
	v_pk_fma_f32 v[104:105], v[18:19], v[172:173], v[170:171] op_sel_hi:[1,0,1] neg_lo:[1,0,0] neg_hi:[1,0,0]
	v_add_f32_e32 v80, v80, v82
	v_add_f32_e32 v82, v81, v80
	v_pk_mul_f32 v[80:81], v[104:105], v[104:105]
	v_pk_fma_f32 v[98:99], v[20:21], v[172:173], v[164:165] op_sel_hi:[1,0,1] neg_lo:[1,0,0] neg_hi:[1,0,0]
	v_add_f32_e32 v80, v80, v82
	v_add_f32_e32 v82, v81, v80
	v_pk_mul_f32 v[80:81], v[98:99], v[98:99]
	v_pk_fma_f32 v[100:101], v[22:23], v[172:173], v[166:167] op_sel_hi:[1,0,1] neg_lo:[1,0,0] neg_hi:[1,0,0]
	v_add_f32_e32 v80, v80, v82
	v_add_f32_e32 v82, v81, v80
	v_pk_mul_f32 v[80:81], v[100:101], v[100:101]
	v_pk_fma_f32 v[88:89], v[24:25], v[172:173], v[160:161] op_sel_hi:[1,0,1] neg_lo:[1,0,0] neg_hi:[1,0,0]
	v_add_f32_e32 v80, v80, v82
	v_add_f32_e32 v82, v81, v80
	v_pk_mul_f32 v[80:81], v[88:89], v[88:89]
	v_pk_fma_f32 v[84:85], v[26:27], v[172:173], v[162:163] op_sel_hi:[1,0,1] neg_lo:[1,0,0] neg_hi:[1,0,0]
	v_add_f32_e32 v80, v80, v82
	v_add_f32_e32 v82, v81, v80
	v_pk_mul_f32 v[80:81], v[84:85], v[84:85]
	s_nop 0
	v_add_f32_e32 v80, v80, v82
	v_add_f32_e32 v132, v81, v80
	v_pk_fma_f32 v[80:81], v[28:29], v[172:173], v[144:145] op_sel_hi:[1,0,1] neg_lo:[1,0,0] neg_hi:[1,0,0]
	s_nop 0
	v_pk_mul_f32 v[82:83], v[80:81], v[80:81]
	s_nop 0
	v_add_f32_e32 v82, v82, v132
	v_add_f32_e32 v134, v83, v82
	v_pk_fma_f32 v[82:83], v[30:31], v[172:173], v[146:147] op_sel_hi:[1,0,1] neg_lo:[1,0,0] neg_hi:[1,0,0]
	s_nop 0
	v_pk_mul_f32 v[132:133], v[82:83], v[82:83]
	s_nop 0
	v_add_f32_e32 v132, v132, v134
	v_add_f32_e32 v132, v133, v132
	s_cbranch_execz .LBB0_453
	s_branch .LBB0_454

; __global__ void __launch_bounds__(NTHREADS, 2) mega_fwd(Args args) {
	.amdhsa_kernel _Z8mega_fwd4Args
		.amdhsa_group_segment_fixed_size 0
		.amdhsa_private_segment_fixed_size 0
		.amdhsa_kernarg_size 448
		.amdhsa_user_sgpr_count 2
		.amdhsa_user_sgpr_dispatch_ptr 0
		.amdhsa_user_sgpr_queue_ptr 0
		.amdhsa_user_sgpr_kernarg_segment_ptr 1
		.amdhsa_user_sgpr_dispatch_id 0
		.amdhsa_user_sgpr_kernarg_preload_length 0
		.amdhsa_user_sgpr_kernarg_preload_offset 0
		.amdhsa_user_sgpr_private_segment_size 0
		.amdhsa_uses_dynamic_stack 0
		.amdhsa_enable_private_segment 0
		.amdhsa_system_sgpr_workgroup_id_x 1
		.amdhsa_system_sgpr_workgroup_id_y 0
		.amdhsa_system_sgpr_workgroup_id_z 0
		.amdhsa_system_sgpr_workgroup_info 0
		.amdhsa_system_vgpr_workitem_id 2
		.amdhsa_next_free_vgpr 251
		.amdhsa_next_free_sgpr 102
		.amdhsa_accum_offset 252
		.amdhsa_reserve_vcc 1
		.amdhsa_float_round_mode_32 0
		.amdhsa_float_round_mode_16_64 0
		.amdhsa_float_denorm_mode_32 3
		.amdhsa_float_denorm_mode_16_64 3
		.amdhsa_dx10_clamp 1
		.amdhsa_ieee_mode 1
		.amdhsa_fp16_overflow 0
		.amdhsa_tg_split 0
		.amdhsa_exception_fp_ieee_invalid_op 0
		.amdhsa_exception_fp_denorm_src 0
		.amdhsa_exception_fp_ieee_div_zero 0
		.amdhsa_exception_fp_ieee_overflow 0
		.amdhsa_exception_fp_ieee_underflow 0
		.amdhsa_exception_fp_ieee_inexact 0
		.amdhsa_exception_int_div_zero 0
	.end_amdhsa_kernel

; __global__ void __launch_bounds__(NTHREADS, 2) mega_fwd(Args args) {
amdhsa.kernels:
  - .agpr_count:     0
    .args:
      - .offset:         0
        .size:           192
        .value_kind:     by_value
      - .offset:         192
        .size:           4
        .value_kind:     hidden_block_count_x
      - .offset:         196
        .size:           4
        .value_kind:     hidden_block_count_y
      - .offset:         200
        .size:           4
        .value_kind:     hidden_block_count_z
      - .offset:         204
        .size:           2
        .value_kind:     hidden_group_size_x
      - .offset:         206
        .size:           2
        .value_kind:     hidden_group_size_y
      - .offset:         208
        .size:           2
        .value_kind:     hidden_group_size_z
      - .offset:         210
        .size:           2
        .value_kind:     hidden_remainder_x
      - .offset:         212
        .size:           2
        .value_kind:     hidden_remainder_y
      - .offset:         214
        .size:           2
        .value_kind:     hidden_remainder_z
      - .offset:         232
        .size:           8
        .value_kind:     hidden_global_offset_x
      - .offset:         240
        .size:           8
        .value_kind:     hidden_global_offset_y
      - .offset:         248
        .size:           8
        .value_kind:     hidden_global_offset_z
      - .offset:         256
        .size:           2
        .value_kind:     hidden_grid_dims
      - .offset:         280
        .size:           8
        .value_kind:     hidden_multigrid_sync_arg
      - .offset:         312
        .size:           4
        .value_kind:     hidden_dynamic_lds_size
    .group_segment_fixed_size: 0
    .kernarg_segment_align: 8
    .kernarg_segment_size: 448
    .language:       OpenCL C
    .language_version:
      - 2
      - 0
    .max_flat_workgroup_size: 512
    .name:           _Z8mega_fwd4Args
    .private_segment_fixed_size: 0
    .sgpr_count:     108
    .sgpr_spill_count: 29
    .symbol:         _Z8mega_fwd4Args.kd
    .uniform_work_group_size: 1
    .uses_dynamic_stack: false
    .vgpr_count:     251
    .vgpr_spill_count: 0
    .wavefront_size: 64
